# lower MFMA-wave priority after the B1/B3 barriers instead of before them
# baseline (speedup 1.0000x reference)
.Lfh:
	s_setprio 1
	s_waitcnt lgkmcnt(8)
	v_mfma_f32_32x32x16_bf16 v[64:79], v[168:171], v[80:83], v[238:253]
	ds_read_b128 v[180:183], v237 offset:53248
	ds_read_b128 v[176:179], v237 offset:53280
	v_add_u32_e32 v172, vcc_lo, v229
	v_add_u32_e32 v218, vcc_lo, v233
	v_mfma_f32_32x32x16_bf16 v[64:79], v[160:163], v[84:87], v[64:79]
	ds_read_b128 v[196:199], v237 offset:57856
	ds_read_b128 v[188:191], v237 offset:62464
	v_mfma_f32_32x32x16_bf16 v[64:79], v[164:167], v[88:91], v[64:79]
	ds_read_b128 v[200:203], v217 offset:13824
	ds_read_b128 v[184:187], v217 offset:13856
	v_mfma_f32_32x32x16_bf16 v[64:79], v[152:155], v[92:95], v[64:79]
	ds_read_b128 v[204:207], v237 offset:57888
	ds_read_b128 v[192:195], v237 offset:62496
	s_waitcnt lgkmcnt(8)
	v_mfma_f32_32x32x16_bf16 v[64:79], v[156:159], v[96:99], v[64:79]
	ds_read_b128 v[168:171], v172 offset:8704
	ds_read_b128 v[160:163], v172 offset:8736
	v_mfma_f32_32x32x16_bf16 v[64:79], v[128:131], v[100:103], v[64:79]
	ds_read_b128 v[164:167], v172 offset:8768
	ds_read_b128 v[152:155], v172 offset:8800
	v_mfma_f32_32x32x16_bf16 v[64:79], v[132:135], v[104:107], v[64:79]
	ds_read_b128 v[156:159], v172 offset:8832
	ds_read_b128 v[128:131], v172 offset:8864
	v_mfma_f32_32x32x16_bf16 v[64:79], v[136:139], v[108:111], v[64:79]
	ds_read_b128 v[132:135], v172 offset:8896
	ds_read_b128 v[136:139], v172 offset:8928
	v_mfma_f32_32x32x16_bf16 v[64:79], v[140:143], v[112:115], v[64:79]
	ds_read_b128 v[140:143], v218 offset:22016
	ds_read_b128 v[172:175], v218 offset:22112
	v_mfma_f32_32x32x16_bf16 v[64:79], v[144:147], v[116:119], v[64:79]
	ds_read_b128 v[144:147], v218 offset:22048
	v_mfma_f32_32x32x16_bf16 v[64:79], v[148:151], v[120:123], v[64:79]
	ds_read_b128 v[148:151], v218 offset:22080
	v_mfma_f32_32x32x16_bf16 v[64:79], v[208:211], v[124:127], v[64:79]
	s_barrier
	s_setprio 0
	s_and_b64 vcc, exec, s[68:69]
	s_cbranch_vccnz .Ldmq_end
	s_cmp_ge_u32 s85, 4
	s_cbranch_scc1 .Lxdq_y
	s_and_b32 s99, s34, 1
	s_mul_i32 s98, s99, 0x4800
	s_addk_i32 s98, 0x6800
	s_mulk_i32 s99, 0x6800
	s_add_i32 s99, s99, s44
	s_add_i32 s98, s98, s44
	s_lshl_b32 s94, s34, 18
	s_lshl_b32 s90, s34, 13
	s_lshl_b32 s91, s34, 7
	s_add_i32 m0, s99, 0x0
	v_add_u32_e32 v255, s94, v221
	global_load_lds_dwordx4 v255, s[8:9]
	s_add_i32 m0, s99, 0x1000
	v_add_u32_e32 v255, s94, v222
	global_load_lds_dwordx4 v255, s[8:9]
	s_add_i32 m0, s99, 0x2000
	v_add_u32_e32 v255, s94, v223
	global_load_lds_dwordx4 v255, s[8:9]
	s_add_i32 m0, s99, 0x3000
	v_add_u32_e32 v255, s94, v224
	global_load_lds_dwordx4 v255, s[8:9]
	s_lshl_b32 s92, s34, s95
	s_add_i32 m0, s99, 0x4000
	v_add_u32_e32 v255, s92, v225
	global_load_lds_dwordx4 v255, s[46:47]
	s_add_i32 m0, s99, 0x5000
	v_add_u32_e32 v255, s90, v226
	global_load_lds_dwordx4 v255, s[52:53]
	s_branch .Ldmq_end

.LBB0_1283:
	v_exp_f32_e32 v64, v64
	v_exp_f32_e32 v65, v65
	v_exp_f32_e32 v66, v66
	v_exp_f32_e32 v67, v67
	v_exp_f32_e32 v68, v68
	v_add_f32_e32 v208, v64, v65
	v_exp_f32_e32 v69, v69
	v_exp_f32_e32 v70, v70
	v_add_f32_e32 v208, v66, v208
	v_exp_f32_e32 v71, v71
	v_add_f32_e32 v208, v67, v208
	v_exp_f32_e32 v72, v72
	v_add_f32_e32 v208, v68, v208
	v_exp_f32_e32 v73, v73
	v_add_f32_e32 v208, v69, v208
	v_exp_f32_e32 v74, v74
	v_add_f32_e32 v208, v70, v208
	v_exp_f32_e32 v75, v75
	v_add_f32_e32 v208, v71, v208
	v_exp_f32_e32 v76, v76
	v_add_f32_e32 v208, v72, v208
	v_exp_f32_e32 v77, v77
	v_add_f32_e32 v208, v73, v208
	v_exp_f32_e32 v78, v78
	v_add_f32_e32 v208, v74, v208
	v_exp_f32_e32 v79, v79
	v_add_f32_e32 v208, v75, v208
	v_add_f32_e32 v208, v76, v208
	v_add_f32_e32 v208, v77, v208
	v_add_f32_e32 v208, v78, v208
	v_add_f32_e32 v208, v79, v208
	v_add_f32_e32 v235, v235, v208
	v_cvt_pk_bf16_f32 v64, v64, v65
	v_cvt_pk_bf16_f32 v65, v66, v67
	v_cvt_pk_bf16_f32 v66, v68, v69
	v_cvt_pk_bf16_f32 v67, v70, v71
	v_cvt_pk_bf16_f32 v68, v72, v73
	v_cvt_pk_bf16_f32 v69, v74, v75
	v_cvt_pk_bf16_f32 v70, v76, v77
	v_cvt_pk_bf16_f32 v71, v78, v79
	s_waitcnt lgkmcnt(0)
	s_setprio 1
	s_barrier
	v_mfma_f32_32x32x16_bf16 v[48:63], v[180:183], v[64:67], v[48:63]
	v_mfma_f32_32x32x16_bf16 v[32:47], v[196:199], v[64:67], v[32:47]
	v_mfma_f32_32x32x16_bf16 v[16:31], v[188:191], v[64:67], v[16:31]
	v_mfma_f32_32x32x16_bf16 v[0:15], v[200:203], v[64:67], v[0:15]
	v_mfma_f32_32x32x16_bf16 v[48:63], v[176:179], v[68:71], v[48:63]
	v_mfma_f32_32x32x16_bf16 v[32:47], v[204:207], v[68:71], v[32:47]
	v_mfma_f32_32x32x16_bf16 v[16:31], v[192:195], v[68:71], v[16:31]
	v_mfma_f32_32x32x16_bf16 v[0:15], v[184:187], v[68:71], v[0:15]
	s_setprio 0
	s_setprio 1
	v_mfma_f32_32x32x16_bf16 v[64:79], v[168:171], v[80:83], v[238:253]
	ds_read_b128 v[180:183], v237 offset:53312
	v_mfma_f32_32x32x16_bf16 v[64:79], v[160:163], v[84:87], v[64:79]
	ds_read_b128 v[176:179], v237 offset:53344
	v_mfma_f32_32x32x16_bf16 v[64:79], v[164:167], v[88:91], v[64:79]
	ds_read_b128 v[184:187], v237 offset:57920
	v_mfma_f32_32x32x16_bf16 v[64:79], v[152:155], v[92:95], v[64:79]
	ds_read_b128 v[192:195], v237 offset:62528
	v_mfma_f32_32x32x16_bf16 v[64:79], v[156:159], v[96:99], v[64:79]
	ds_read_b128 v[196:199], v217 offset:13888
	v_mfma_f32_32x32x16_bf16 v[64:79], v[128:131], v[100:103], v[64:79]
	ds_read_b128 v[188:191], v217 offset:13920
	v_mfma_f32_32x32x16_bf16 v[64:79], v[132:135], v[104:107], v[64:79]
	ds_read_b128 v[200:203], v237 offset:57952
	v_mfma_f32_32x32x16_bf16 v[64:79], v[136:139], v[108:111], v[64:79]
	ds_read_b128 v[204:207], v237 offset:62560
	v_mfma_f32_32x32x16_bf16 v[64:79], v[140:143], v[112:115], v[64:79]
	v_mfma_f32_32x32x16_bf16 v[64:79], v[144:147], v[116:119], v[64:79]
	v_mfma_f32_32x32x16_bf16 v[64:79], v[148:151], v[120:123], v[64:79]
	v_mfma_f32_32x32x16_bf16 v[64:79], v[172:175], v[124:127], v[64:79]
	s_waitcnt vmcnt(0) lgkmcnt(0)
	s_barrier
	s_setprio 0
	s_add_i32 vcc_lo, s15, 63
	s_cmp_le_i32 vcc_lo, s86
	s_cbranch_scc1 .LBB0_1285
	v_add_u32_e32 v208, s15, v232
	v_add_u32_e32 v237, 32, v208
	v_cmp_lt_i32_e32 vcc, v237, v228
	s_nop 5
	v_cndmask_b32_e32 v65, v213, v65, vcc
	v_cmp_le_i32_e32 vcc, v237, v228
	v_add_u32_e32 v237, 34, v208
	s_nop 0
	v_cndmask_b32_e32 v64, v213, v64, vcc
	v_cmp_le_i32_e32 vcc, v237, v228
	v_add_u32_e32 v237, 35, v208
	s_nop 0
	v_cndmask_b32_e32 v66, v213, v66, vcc
	v_cmp_le_i32_e32 vcc, v237, v228
	v_add_u32_e32 v237, 40, v208
	s_nop 0
	v_cndmask_b32_e32 v67, v213, v67, vcc
	v_cmp_le_i32_e32 vcc, v237, v228
	v_add_u32_e32 v237, 41, v208
	s_nop 0
	v_cndmask_b32_e32 v68, v213, v68, vcc
	v_cmp_le_i32_e32 vcc, v237, v228
	v_add_u32_e32 v237, 42, v208
	s_nop 0
	v_cndmask_b32_e32 v69, v213, v69, vcc
	v_cmp_le_i32_e32 vcc, v237, v228
	v_add_u32_e32 v237, 43, v208
	s_nop 0
	v_cndmask_b32_e32 v70, v213, v70, vcc
	v_cmp_le_i32_e32 vcc, v237, v228
	v_add_u32_e32 v237, 48, v208
	s_nop 0
	v_cndmask_b32_e32 v71, v213, v71, vcc
	v_cmp_le_i32_e32 vcc, v237, v228
	v_add_u32_e32 v237, 49, v208
	s_nop 0
	v_cndmask_b32_e32 v72, v213, v72, vcc
	v_cmp_le_i32_e32 vcc, v237, v228
	v_add_u32_e32 v237, 50, v208
	s_nop 0
	v_cndmask_b32_e32 v73, v213, v73, vcc
	v_cmp_le_i32_e32 vcc, v237, v228
	v_add_u32_e32 v237, 51, v208
	s_nop 0
	v_cndmask_b32_e32 v74, v213, v74, vcc
	v_cmp_le_i32_e32 vcc, v237, v228
	v_add_u32_e32 v237, 56, v208
	s_nop 0
	v_cndmask_b32_e32 v75, v213, v75, vcc
	v_cmp_le_i32_e32 vcc, v237, v228
	v_add_u32_e32 v237, 57, v208
	s_nop 0
	v_cndmask_b32_e32 v76, v213, v76, vcc
	v_cmp_le_i32_e32 vcc, v237, v228
	v_add_u32_e32 v237, 58, v208
	v_add_u32_e32 v208, 59, v208
	v_cndmask_b32_e32 v77, v213, v77, vcc
	v_cmp_le_i32_e32 vcc, v237, v228
	s_nop 1
	v_cndmask_b32_e32 v78, v213, v78, vcc
	v_cmp_le_i32_e32 vcc, v208, v228
	s_nop 1
	v_cndmask_b32_e32 v79, v213, v79, vcc
